# v27 + selected-loop interior tile: all eight K fragments requested up front, QK chains run back to back with counted waits
# speedup vs baseline: 1.0026x; 1.0026x over previous
.LBB0_878:
	v_mov_b32_e32 v0, v165
	s_lshl_b32 s2, s30, 6
	v_ashrrev_i32_e32 v34, 3, v0
	v_add_u32_e32 v34, s2, v34
	v_ashrrev_i32_e32 v35, 31, v34
	v_lshlrev_b64 v[34:35], 11, v[34:35]
	v_lshlrev_b32_e32 v0, 4, v0
	v_lshl_add_u64 v[34:35], s[14:15], 0, v[34:35]
	v_and_b32_e32 v0, 0x70, v0
	v_lshl_add_u64 v[34:35], v[34:35], 0, v[0:1]
	v_mov_b32_e32 v0, v165
	global_load_dwordx4 v[90:93], v[34:35], off
	s_nop 0
	v_ashrrev_i32_e32 v34, 3, v0
	v_add_u32_e32 v34, s2, v34
	v_ashrrev_i32_e32 v35, 31, v34
	v_lshlrev_b64 v[34:35], 11, v[34:35]
	v_lshlrev_b32_e32 v0, 4, v0
	v_lshl_add_u64 v[34:35], s[16:17], 0, v[34:35]
	v_and_b32_e32 v0, 0x70, v0
	v_lshl_add_u64 v[34:35], v[34:35], 0, v[0:1]
	global_load_dwordx4 v[94:97], v[34:35], off
	s_ashr_i32 s2, s67, 6
	v_lshl_add_u32 v0, s2, 3, v185
	ds_read_b64 v[34:35], v0 offset:59904
	s_waitcnt lgkmcnt(0)
	v_lshrrev_b64 v[34:35], s67, v[34:35]
	v_and_b32_e32 v0, 1, v34
	v_cmp_eq_u32_e64 s[10:11], 1, v0
	v_cmp_ne_u32_e32 vcc, 0, v0
	s_cbranch_vccz .LBB0_888
	s_lshl_b32 s3, s67, 6
	s_or_b32 s2, s3, 63
	s_cmp_gt_i32 s2, s25
	s_mul_i32 s2, s64, 0x2400
	v_add_u32_e32 v192, s2, v184
	ds_read_b128 v[98:101], v192
	ds_read_b128 v[102:105], v192 offset:32
	ds_read_b128 v[106:109], v192 offset:64
	ds_read_b128 v[110:113], v192 offset:96
	v_add_u32_e32 v0, s3, v120
	s_mul_i32 s2, s64, 0x3000
	s_mov_b64 s[18:19], -1
	v_sub_u32_e32 v190, v187, v0
	s_cbranch_scc1 .LBB0_883
	ds_read_b128 v[238:241], v192 offset:4608
	ds_read_b128 v[242:245], v192 offset:4640
	ds_read_b128 v[246:249], v192 offset:4672
	ds_read_b128 v[250:253], v192 offset:4704
	v_mov_b32_e32 v0, v190
	v_mov_b32_e32 v229, v188
	s_waitcnt lgkmcnt(7)
	v_mfma_f32_32x32x16_bf16 v[50:65], v[98:101], v[66:69], v[194:209]
	v_cvt_f32_i32_e32 v231, v0
	s_waitcnt lgkmcnt(6)
	v_mfma_f32_32x32x16_bf16 v[50:65], v[102:105], v[70:73], v[50:65]
	s_waitcnt lgkmcnt(5)
	v_mfma_f32_32x32x16_bf16 v[50:65], v[106:109], v[74:77], v[50:65]
	s_waitcnt lgkmcnt(4)
	v_mfma_f32_32x32x16_bf16 v[50:65], v[110:113], v[78:81], v[50:65]
	s_waitcnt lgkmcnt(3)
	v_mfma_f32_32x32x16_bf16 v[34:49], v[238:241], v[66:69], v[210:225]
	s_waitcnt lgkmcnt(2)
	v_mfma_f32_32x32x16_bf16 v[34:49], v[242:245], v[70:73], v[34:49]
	s_waitcnt lgkmcnt(1)
	v_mfma_f32_32x32x16_bf16 v[34:49], v[246:249], v[74:77], v[34:49]
	s_waitcnt lgkmcnt(0)
	v_mfma_f32_32x32x16_bf16 v[34:49], v[250:253], v[78:81], v[34:49]
	s_nop 3
	v_max3_f32 v0, v50, s28, v51
	v_max3_f32 v0, v0, v52, v53
	v_max3_f32 v0, v0, v54, v55
	v_max3_f32 v0, v0, v56, v57
	v_max3_f32 v0, v0, v58, v59
	v_max3_f32 v0, v0, v60, v61
	v_max3_f32 v0, v0, v62, v63
	v_max3_f32 v0, v0, v64, v65
	s_nop 3
	v_max3_f32 v0, v0, v34, v35
	v_max3_f32 v0, v0, v36, v37
	v_max3_f32 v0, v0, v38, v39
	v_max3_f32 v0, v0, v40, v41
	v_max3_f32 v0, v0, v42, v43
	v_max3_f32 v0, v0, v44, v45
	v_max3_f32 v0, v0, v46, v47
	v_max3_f32 v0, v0, v48, v49
	v_fma_f32 v0, -v118, v231, v0
	v_cndmask_b32_e64 v0, v144, v0, s[10:11]
	ds_bpermute_b32 v230, v186, v0
	s_waitcnt lgkmcnt(0)
	v_max3_f32 v0, v189, v0, v230
	v_cmp_gt_f32_e32 vcc, v0, v189
	s_cbranch_vccz .LBB0_882
	v_sub_f32_e32 v230, v189, v0
	v_exp_f32_e32 v230, v230
	s_nop 0
	v_mul_f32_e32 v229, v188, v230
	v_pk_mul_f32 v[32:33], v[32:33], v[230:231] op_sel_hi:[1,0]
	v_pk_mul_f32 v[30:31], v[30:31], v[230:231] op_sel_hi:[1,0]
	v_pk_mul_f32 v[28:29], v[28:29], v[230:231] op_sel_hi:[1,0]
	v_pk_mul_f32 v[26:27], v[26:27], v[230:231] op_sel_hi:[1,0]
	v_pk_mul_f32 v[24:25], v[24:25], v[230:231] op_sel_hi:[1,0]
	v_pk_mul_f32 v[22:23], v[22:23], v[230:231] op_sel_hi:[1,0]
	v_pk_mul_f32 v[20:21], v[20:21], v[230:231] op_sel_hi:[1,0]
	v_pk_mul_f32 v[18:19], v[18:19], v[230:231] op_sel_hi:[1,0]
	v_pk_mul_f32 v[16:17], v[16:17], v[230:231] op_sel_hi:[1,0]
	v_pk_mul_f32 v[14:15], v[14:15], v[230:231] op_sel_hi:[1,0]
	v_pk_mul_f32 v[12:13], v[12:13], v[230:231] op_sel_hi:[1,0]
	v_pk_mul_f32 v[10:11], v[10:11], v[230:231] op_sel_hi:[1,0]
	v_pk_mul_f32 v[8:9], v[8:9], v[230:231] op_sel_hi:[1,0]
	v_pk_mul_f32 v[6:7], v[6:7], v[230:231] op_sel_hi:[1,0]
	v_pk_mul_f32 v[4:5], v[4:5], v[230:231] op_sel_hi:[1,0]
	v_pk_mul_f32 v[2:3], v[2:3], v[230:231] op_sel_hi:[1,0]
